# v17 plus odd WGs enter the input projection 8us late
# baseline (speedup 1.0000x reference)
;     __device__ void init(int M, int N, int G_, int c_, unsigned long long mask_ = 0ull) { nM = M / BM; nN = mask_ ? __builtin_popcountll(mask_) : N / BM; nwg = nM * nN; G = G_; c = c_; mask = mask_; }
; #define LAUNDER() do { tid = threadIdx.x; asm volatile("" : "+v"(tid)); lane = tid & 63; wid = __builtin_amdgcn_readfirstlane(tid >> 6); bx = blockIdx.x; asm volatile("" : "+s"(bx)); \
;         vcu = (G % 8 == 0) ? (bx % 8) * (G / 8) + bx / 8 : bx; gw = vcu * 8 + wid; ws = P.ws; asm volatile("" : "+s"(ws)); Q.ws = ws; XB = (bf16_t*)(ws + WS_XB); } while (0)
; __global__ void __launch_bounds__(512, 2) trunk_fwd(Params P) {
;     ...
;         LAUNDER();
;         {
;             pg8::Gemm g{(const bf16_t*)(ws + WS_XB8), (const bf16_t*)(ws + WS_WIN), T, NCOLS, DM / 2, 2}; pg8::StaticOrder S; S.init(T, NCOLS, G, bx, FP8_TILES);
;             Epi<EPI_INPROJ> E{}; E.ws = ws; E.sc_all = 1.0f / 64.0f;
;             pg8::gemm_phase<Epi<EPI_INPROJ>, pg8::StaticOrder, true>(lds, g, S, E); }
.LBB0_106:
	v_mov_b32_e32 v0, v160
	v_readlane_b32 s0, v252, 50
	s_nop 3
	s_bitcmp1_b32 s0, 0
	s_cbranch_scc0 .Lstagger_p1_done
	s_sleep 127
	s_sleep 127
.Lstagger_p1_done:
	s_mov_b64 s[2:3], s[44:45]
	s_add_u32 s1, s2, 0x100000
	s_addc_u32 s8, s3, 0
	v_mov_b32_e32 v8, v160
	s_cmpk_gt_i32 s0, 0xdff
	v_readfirstlane_b32 s14, v8
	s_mov_b32 s72, s56
	s_mov_b64 s[64:65], s[42:43]
	s_mov_b64 s[74:75], s[60:61]
	s_cbranch_scc1 .LBB0_136
	s_ashr_i32 s9, s0, 31
	s_lshr_b32 s4, s9, 29
	s_add_i32 s4, s0, s4
	s_ashr_i32 s6, s4, 3
	s_and_b32 s4, s4, -8
	s_sub_i32 s4, s0, s4
	s_cmp_lt_i32 s4, 0
	s_movk_i32 s7, 0x1c1
	s_cselect_b32 s7, s7, 0x1c0
	s_mul_i32 s4, s4, s7
	s_add_i32 s6, s4, s6
	s_mul_hi_i32 s4, s6, 0x92492493
	s_add_i32 s4, s4, s6
	s_lshr_b32 s7, s4, 31
	s_ashr_i32 s4, s4, 7
	s_add_i32 s4, s4, s7
	s_mul_i32 s7, s4, 0xe0
	s_sub_i32 s15, s6, s7
	s_bfe_u32 s6, s15, 0x3001c
	s_add_i32 s6, s15, s6
	s_sext_i32_i16 s6, s6
	s_lshr_b32 s16, s6, 3
	s_cmp_lt_i32 s15, 8
	s_mov_b64 s[38:39], 2
	s_cbranch_scc1 .LBB0_111
	s_mov_b32 s6, 0xfff0f0cc
	s_sext_i32_i16 s10, s16
	s_movk_i32 s7, 0xff
